# plus FFN1 epilogue redundant canonicalising max removed; cumsum rows moved to the workgroups without k-norm units
# speedup vs baseline: 1.0031x; 1.0031x over previous
; DI int opaque_tid() { int t = threadIdx.x; asm volatile("" : "+v"(t)); return t; }
; DI void ph_cumsum(const Params& p, bf16_t* smem) {
;     float* sm = (float*)smem;
;     const int tid = opaque_tid(), lane = tid & 63, w = tid >> 6;
;     const float* LF = (const float*)(p.ws + OFF_LOGF);
;     float* CF = (float*)(p.ws + OFF_CUMF);
;     for (int it = blockIdx.x; it < 32; it += gridDim.x) {
;         const float* src = LF + (size_t)it * LP; float* dst = CF + (size_t)it * LP;
;         const int p0 = tid * 17;
;         float v[17];
; #pragma unroll
;         for (int i = 0; i < 17; ++i) { const int pos = p0 + i; v[i] = (pos < LT) ? src[pos] : 0.f; }
;         float s = 0.f;
; #pragma unroll
;         for (int i = 0; i < 17; ++i) s += v[i];
;         float incl = s;
; #pragma unroll
;         for (int o = 1; o < 64; o <<= 1) { const float t = __shfl_up(incl, o); if (lane >= o) incl += t; }
.LBB0_470:
	s_or_b64 exec, exec, s[0:1]
	s_add_u32 s35, s56, 0xf964000
	s_addc_u32 s76, s57, 0
	s_cmp_lt_i32 s2, 32
	s_cselect_b64 s[0:1], -1, 0
	v_mov_b32_e32 v9, v210
	v_writelane_b32 v252, s0, 2
	s_add_i32 s3, s58, -28
	s_sub_i32 s3, s2, s3
	s_cmp_lt_i32 s3, 0
	s_waitcnt lgkmcnt(0)
	s_barrier
	v_writelane_b32 v252, s1, 3
	s_cbranch_scc1 .LBB0_535
	v_mbcnt_lo_u32_b32 v1, -1, 0
	s_movk_i32 s3, 0x1e3
	v_mbcnt_hi_u32_b32 v8, -1, v1
	v_cmp_gt_i32_e64 s[4:5], s3, v9
	s_movk_i32 s3, 0x1e2
	v_and_b32_e32 v12, 64, v8
	v_cmp_gt_i32_e64 s[6:7], s3, v9
	v_add_u32_e32 v3, -1, v8
	v_add_u32_e32 v4, -2, v8
	v_add_u32_e32 v5, -4, v8
	v_add_u32_e32 v6, -8, v8
	v_add_u32_e32 v7, -16, v8
	v_subrev_u32_e32 v13, 32, v8
	s_movk_i32 s3, 0x1ea
	v_ashrrev_i32_e32 v10, 6, v9
	v_cmp_lt_i32_e64 s[8:9], v3, v12
	v_cmp_lt_i32_e64 s[10:11], v4, v12
	v_cmp_lt_i32_e64 s[12:13], v5, v12
	v_cmp_lt_i32_e64 s[14:15], v6, v12
	v_cmp_lt_i32_e64 s[16:17], v7, v12
	v_cmp_lt_i32_e64 s[18:19], v13, v12
	v_cmp_gt_i32_e64 s[20:21], s3, v9
	s_movk_i32 s3, 0x1e9
	v_and_b32_e32 v11, 63, v9
	v_lshl_add_u32 v0, v9, 4, v9
	v_cndmask_b32_e64 v3, v3, v8, s[8:9]
	v_cndmask_b32_e64 v4, v4, v8, s[10:11]
	v_cndmask_b32_e64 v5, v5, v8, s[12:13]
	v_cndmask_b32_e64 v6, v6, v8, s[14:15]
	v_cndmask_b32_e64 v7, v7, v8, s[16:17]
	v_cndmask_b32_e64 v8, v13, v8, s[18:19]
	v_cmp_gt_i32_e64 s[22:23], s3, v9
	v_and_b32_e32 v9, 7, v10
	v_cmp_eq_u32_e32 vcc, 63, v11
	v_lshl_add_u32 v2, v10, 2, 0
	v_cmp_lt_i32_e64 s[0:1], 0, v10
	v_ashrrev_i32_e32 v1, 31, v0
	v_lshlrev_b32_e32 v3, 2, v3
	v_cmp_eq_u32_e64 s[8:9], 0, v11
	v_lshlrev_b32_e32 v4, 2, v4
	v_cmp_gt_u32_e64 s[10:11], 2, v11
	v_lshlrev_b32_e32 v5, 2, v5
	v_cmp_gt_u32_e64 s[12:13], 4, v11
	v_lshlrev_b32_e32 v6, 2, v6
	v_cmp_gt_u32_e64 s[14:15], 8, v11
	v_lshlrev_b32_e32 v7, 2, v7
	v_cmp_gt_u32_e64 s[16:17], 16, v11
	v_lshlrev_b32_e32 v8, 2, v8
	v_cmp_gt_u32_e64 s[18:19], 32, v11
	v_cmp_lt_u32_e64 s[24:25], 7, v10
	v_and_b32_e32 v10, 0x7ffffff8, v10
	v_cmp_ne_u32_e64 s[26:27], 0, v9
	s_add_i32 s3, s58, -28
	s_sub_i32 s3, s2, s3
	s_branch .LBB0_473
.LBB0_472:
	s_or_b64 exec, exec, s[50:51]
	s_add_i32 s3, s3, 28
	s_cmp_lt_i32 s3, 32
	s_cbranch_scc0 .LBB0_535

; DI bf16_t f2bf(float x) { return (bf16_t)(cvt_pk(x, 0.f) & 0xffffu); }
; DI float ex2(float x) { return __builtin_amdgcn_exp2f(x); }
;     ...
;     } else if (EPI == EPI_FFN1) {
;         bf16_t* d = (bf16_t*)(p.ws + OFF_U) + (size_t)row0 * 4096 + col;
; #pragma unroll
;         for (int e = 0; e < 4; ++e) { const float t = fmaxf(v[e], 0.f); d[(size_t)e * 4096] = f2bf(t * t); }
; template <int EPI, int K, int LNI = -1>
; DI void ph_gemm(const Params& p, const bf16_t* __restrict__ A, const bf16_t* __restrict__ Bt, int N, float* s_aux) {
;     ...
;             for (int ai = 0; ai < 2; ++ai)
; #pragma unroll
;                 for (int m = 0; m < 4; ++m) {
;                     const int lrow0 = ai * 128 + wr * 64 + m * 16 + fq * 4, row0 = brow + lrow0 + oz;
;                     f32x2 rs[4];
;                     if (EPI == EPI_RESID && LNI >= 0) {
;                         const f32x2* st_ = (const f32x2*)((unsigned char*)p.out + OFFO_STATS) + row0;
; #pragma unroll
;                         for (int e = 0; e < 4; ++e) rs[e] = st_[e];
;                     }
;                     if (EPI == EPI_E5) {
;                         const int idx_ = ((row0 % LT) + 48) & 63; const float lgh = lg_[0][0];
; #pragma unroll
;                         for (int e = 0; e < 4; ++e) rs[e] = (f32x2){ex2(lgh * (float)(idx_ + e + 1)), 0.0625f * ex2(lgh * (float)(63 - idx_ - e))};
;                     }
; #pragma unroll
;                     for (int bj = 0; bj < 2; ++bj)
; #pragma unroll
;                         for (int n = 0; n < 2; ++n) {
;                             float v[4];
; #pragma unroll
;                             for (int e = 0; e < 4; ++e) v[e] = acc[ai][bj][m][n][e];
;                             epi_store<EPI, LNI>(p, row0, bcol + bj * 128 + wc * 32 + n * 16 + fr + oz, lrow0, v, sa, rs, lg_[bj][n], lb_[bj][n]);
;                         }
.LBB0_931:
	s_or_b64 exec, exec, s[28:29]
	s_lshl_b32 s15, s26, 8
	v_mov_b32_e32 v137, 0
	v_lshl_or_b32 v138, s24, 8, v155
	v_add3_u32 v136, v154, s15, v137
	v_add_u32_e32 v138, v138, v137
	v_ashrrev_i32_e32 v137, 31, v136
	v_lshlrev_b64 v[166:167], 13, v[136:137]
	v_ashrrev_i32_e32 v139, 31, v138
	v_max_f32_e32 v124, 0, v124
	v_lshl_add_u64 v[166:167], s[36:37], 0, v[166:167]
	v_lshlrev_b64 v[138:139], 1, v[138:139]
	v_mul_f32_e32 v124, v124, v124
	v_max_f32_e32 v112, 0, v112
	v_lshl_add_u64 v[166:167], v[166:167], 0, v[138:139]
	v_cvt_pk_bf16_f32 v124, v124, s0
	v_mul_f32_e32 v112, v112, v112
	global_store_short v[166:167], v124, off
	v_cvt_pk_bf16_f32 v112, v112, s0
	v_max_f32_e32 v124, 0, v125
	global_store_short v[166:167], v112, off offset:288
	v_mul_f32_e32 v124, v124, v124
	v_max_f32_e32 v112, 0, v113
	v_cvt_pk_bf16_f32 v137, v124, s0
	v_add_co_u32_e32 v124, vcc, s3, v166
	v_mul_f32_e32 v112, v112, v112
	s_nop 0
	v_addc_co_u32_e32 v125, vcc, 0, v167, vcc
	v_cvt_pk_bf16_f32 v112, v112, s0
	v_max_f32_e32 v126, 0, v126
	global_store_short v[124:125], v112, off offset:288
	v_mul_f32_e32 v126, v126, v126
	v_add_co_u32_e32 v168, vcc, s25, v166
	v_max_f32_e32 v112, 0, v114
	v_cvt_pk_bf16_f32 v126, v126, s0
	v_addc_co_u32_e32 v169, vcc, 0, v167, vcc
	v_mul_f32_e32 v112, v112, v112
	global_store_short v[168:169], v126, off
	v_cvt_pk_bf16_f32 v112, v112, s0
	v_max_f32_e32 v126, 0, v127
	global_store_short v[168:169], v112, off offset:288
	v_mul_f32_e32 v126, v126, v126
	v_max_f32_e32 v112, 0, v115
	global_store_short v[124:125], v137, off
	v_cvt_pk_bf16_f32 v137, v126, s0
	v_add_co_u32_e32 v126, vcc, s27, v166
	v_mul_f32_e32 v112, v112, v112
	s_nop 0
	v_addc_co_u32_e32 v127, vcc, 0, v167, vcc
	v_cvt_pk_bf16_f32 v112, v112, s0
	global_store_short v[126:127], v112, off offset:288
	v_add_u32_e32 v112, 16, v136
	v_max_f32_e32 v116, 0, v116
	v_ashrrev_i32_e32 v113, 31, v112
	v_mul_f32_e32 v116, v116, v116
	v_lshlrev_b64 v[112:113], 13, v[112:113]
	v_max_f32_e32 v108, 0, v108
	v_cvt_pk_bf16_f32 v116, v116, s0
	v_lshl_add_u64 v[112:113], s[36:37], 0, v[112:113]
	v_mul_f32_e32 v108, v108, v108
	v_max_f32_e32 v96, 0, v96
	global_store_short v[166:167], v116, off offset:256
	v_lshl_add_u64 v[112:113], v[112:113], 0, v[138:139]
	v_cvt_pk_bf16_f32 v108, v108, s0
	v_mul_f32_e32 v96, v96, v96
	v_max_f32_e32 v116, 0, v117
	global_store_short v[112:113], v108, off
	v_cvt_pk_bf16_f32 v96, v96, s0
	v_mul_f32_e32 v116, v116, v116
	v_max_f32_e32 v108, 0, v109
	global_store_short v[112:113], v96, off offset:288
	v_cvt_pk_bf16_f32 v116, v116, s0
	v_mul_f32_e32 v108, v108, v108
	v_max_f32_e32 v96, 0, v97
	global_store_short v[124:125], v116, off offset:256
	v_cvt_pk_bf16_f32 v114, v108, s0
	v_add_co_u32_e32 v108, vcc, s3, v112
	v_mul_f32_e32 v96, v96, v96
	v_max_f32_e32 v116, 0, v118
	v_addc_co_u32_e32 v109, vcc, 0, v113, vcc
	v_cvt_pk_bf16_f32 v96, v96, s0
	v_mul_f32_e32 v116, v116, v116
	v_max_f32_e32 v110, 0, v110
	global_store_short v[108:109], v96, off offset:288
	v_cvt_pk_bf16_f32 v116, v116, s0
	global_store_short v[108:109], v114, off
	v_mul_f32_e32 v110, v110, v110
	v_add_co_u32_e32 v114, vcc, s25, v112
	v_max_f32_e32 v96, 0, v98
	global_store_short v[168:169], v116, off offset:256
	v_cvt_pk_bf16_f32 v110, v110, s0
	v_addc_co_u32_e32 v115, vcc, 0, v113, vcc
	v_mul_f32_e32 v96, v96, v96
	v_max_f32_e32 v116, 0, v119
	global_store_short v[114:115], v110, off
	v_cvt_pk_bf16_f32 v96, v96, s0
	v_mul_f32_e32 v116, v116, v116
	v_max_f32_e32 v110, 0, v111
	global_store_short v[114:115], v96, off offset:288
	v_cvt_pk_bf16_f32 v116, v116, s0
	v_mul_f32_e32 v110, v110, v110
	v_max_f32_e32 v96, 0, v99
	global_store_short v[126:127], v116, off offset:256
	v_cvt_pk_bf16_f32 v116, v110, s0
	v_add_co_u32_e32 v110, vcc, s27, v112
	v_mul_f32_e32 v96, v96, v96
	s_nop 0
	v_addc_co_u32_e32 v111, vcc, 0, v113, vcc
	v_cvt_pk_bf16_f32 v96, v96, s0
	global_store_short v[110:111], v96, off offset:288
	v_add_u32_e32 v96, 32, v136
	v_max_f32_e32 v100, 0, v100
	v_ashrrev_i32_e32 v97, 31, v96
	v_mul_f32_e32 v100, v100, v100
	v_lshlrev_b64 v[96:97], 13, v[96:97]
	v_max_f32_e32 v92, 0, v92
	v_cvt_pk_bf16_f32 v100, v100, s0
	v_lshl_add_u64 v[96:97], s[36:37], 0, v[96:97]
	v_mul_f32_e32 v92, v92, v92
	v_max_f32_e32 v80, 0, v80
	global_store_short v[112:113], v100, off offset:256
	v_lshl_add_u64 v[96:97], v[96:97], 0, v[138:139]
	v_cvt_pk_bf16_f32 v92, v92, s0
	v_mul_f32_e32 v80, v80, v80
	v_max_f32_e32 v100, 0, v101
	global_store_short v[96:97], v92, off
	v_cvt_pk_bf16_f32 v80, v80, s0
	v_mul_f32_e32 v100, v100, v100
	v_max_f32_e32 v92, 0, v93
	global_store_short v[96:97], v80, off offset:288
	v_cvt_pk_bf16_f32 v100, v100, s0
	v_mul_f32_e32 v92, v92, v92
	v_max_f32_e32 v80, 0, v81
	global_store_short v[108:109], v100, off offset:256
	v_cvt_pk_bf16_f32 v98, v92, s0
	v_add_co_u32_e32 v92, vcc, s3, v96
	v_mul_f32_e32 v80, v80, v80
	v_max_f32_e32 v100, 0, v102
	v_addc_co_u32_e32 v93, vcc, 0, v97, vcc
	v_cvt_pk_bf16_f32 v80, v80, s0
	v_mul_f32_e32 v100, v100, v100
	v_max_f32_e32 v94, 0, v94
	global_store_short v[92:93], v80, off offset:288
	v_cvt_pk_bf16_f32 v100, v100, s0
	global_store_short v[92:93], v98, off
	v_mul_f32_e32 v94, v94, v94
	v_add_co_u32_e32 v98, vcc, s25, v96
	v_max_f32_e32 v80, 0, v82
	global_store_short v[114:115], v100, off offset:256
	v_cvt_pk_bf16_f32 v94, v94, s0
	v_addc_co_u32_e32 v99, vcc, 0, v97, vcc
	v_mul_f32_e32 v80, v80, v80
	v_max_f32_e32 v100, 0, v103
	global_store_short v[98:99], v94, off
	v_cvt_pk_bf16_f32 v80, v80, s0
	v_mul_f32_e32 v100, v100, v100
	v_max_f32_e32 v94, 0, v95
	global_store_short v[98:99], v80, off offset:288
	v_cvt_pk_bf16_f32 v100, v100, s0
; DI bf16_t f2bf(float x) { return (bf16_t)(cvt_pk(x, 0.f) & 0xffffu); }
; DI float ex2(float x) { return __builtin_amdgcn_exp2f(x); }
;     ...
;     } else if (EPI == EPI_FFN1) {
;         bf16_t* d = (bf16_t*)(p.ws + OFF_U) + (size_t)row0 * 4096 + col;
; #pragma unroll
;         for (int e = 0; e < 4; ++e) { const float t = fmaxf(v[e], 0.f); d[(size_t)e * 4096] = f2bf(t * t); }
; template <int EPI, int K, int LNI = -1>
; DI void ph_gemm(const Params& p, const bf16_t* __restrict__ A, const bf16_t* __restrict__ Bt, int N, float* s_aux) {
;     ...
;             for (int ai = 0; ai < 2; ++ai)
; #pragma unroll
;                 for (int m = 0; m < 4; ++m) {
;                     const int lrow0 = ai * 128 + wr * 64 + m * 16 + fq * 4, row0 = brow + lrow0 + oz;
;                     f32x2 rs[4];
;                     if (EPI == EPI_RESID && LNI >= 0) {
;                         const f32x2* st_ = (const f32x2*)((unsigned char*)p.out + OFFO_STATS) + row0;
; #pragma unroll
;                         for (int e = 0; e < 4; ++e) rs[e] = st_[e];
;                     }
;                     if (EPI == EPI_E5) {
;                         const int idx_ = ((row0 % LT) + 48) & 63; const float lgh = lg_[0][0];
; #pragma unroll
;                         for (int e = 0; e < 4; ++e) rs[e] = (f32x2){ex2(lgh * (float)(idx_ + e + 1)), 0.0625f * ex2(lgh * (float)(63 - idx_ - e))};
;                     }
; #pragma unroll
;                     for (int bj = 0; bj < 2; ++bj)
; #pragma unroll
;                         for (int n = 0; n < 2; ++n) {
;                             float v[4];
; #pragma unroll
;                             for (int e = 0; e < 4; ++e) v[e] = acc[ai][bj][m][n][e];
;                             epi_store<EPI, LNI>(p, row0, bcol + bj * 128 + wc * 32 + n * 16 + fr + oz, lrow0, v, sa, rs, lg_[bj][n], lb_[bj][n]);
;                         }
	v_mul_f32_e32 v94, v94, v94
	v_max_f32_e32 v80, 0, v83
	global_store_short v[110:111], v100, off offset:256
	v_cvt_pk_bf16_f32 v100, v94, s0
	v_add_co_u32_e32 v94, vcc, s27, v96
	v_mul_f32_e32 v80, v80, v80
	s_nop 0
	v_addc_co_u32_e32 v95, vcc, 0, v97, vcc
	v_cvt_pk_bf16_f32 v80, v80, s0
	global_store_short v[94:95], v80, off offset:288
	v_add_u32_e32 v80, 48, v136
	v_max_f32_e32 v84, 0, v84
	v_ashrrev_i32_e32 v81, 31, v80
	v_mul_f32_e32 v84, v84, v84
	v_lshlrev_b64 v[80:81], 13, v[80:81]
	v_max_f32_e32 v76, 0, v76
	v_cvt_pk_bf16_f32 v84, v84, s0
	v_lshl_add_u64 v[80:81], s[36:37], 0, v[80:81]
	v_mul_f32_e32 v76, v76, v76
	v_max_f32_e32 v64, 0, v64
	global_store_short v[96:97], v84, off offset:256
	v_lshl_add_u64 v[80:81], v[80:81], 0, v[138:139]
	v_cvt_pk_bf16_f32 v76, v76, s0
	v_mul_f32_e32 v64, v64, v64
	v_max_f32_e32 v84, 0, v85
	global_store_short v[80:81], v76, off
	v_cvt_pk_bf16_f32 v64, v64, s0
	v_mul_f32_e32 v84, v84, v84
	v_max_f32_e32 v76, 0, v77
	global_store_short v[80:81], v64, off offset:288
	v_cvt_pk_bf16_f32 v84, v84, s0
	v_mul_f32_e32 v76, v76, v76
	v_max_f32_e32 v64, 0, v65
	global_store_short v[92:93], v84, off offset:256
	v_cvt_pk_bf16_f32 v82, v76, s0
	v_add_co_u32_e32 v76, vcc, s3, v80
	v_mul_f32_e32 v64, v64, v64
	v_max_f32_e32 v84, 0, v86
	v_addc_co_u32_e32 v77, vcc, 0, v81, vcc
	v_cvt_pk_bf16_f32 v64, v64, s0
	v_mul_f32_e32 v84, v84, v84
	v_max_f32_e32 v78, 0, v78
	global_store_short v[76:77], v64, off offset:288
	v_cvt_pk_bf16_f32 v84, v84, s0
	global_store_short v[76:77], v82, off
	v_mul_f32_e32 v78, v78, v78
	v_add_co_u32_e32 v82, vcc, s25, v80
	v_max_f32_e32 v64, 0, v66
	global_store_short v[98:99], v84, off offset:256
	v_cvt_pk_bf16_f32 v78, v78, s0
	v_addc_co_u32_e32 v83, vcc, 0, v81, vcc
	v_mul_f32_e32 v64, v64, v64
	v_max_f32_e32 v84, 0, v87
	global_store_short v[82:83], v78, off
	v_cvt_pk_bf16_f32 v64, v64, s0
	v_mul_f32_e32 v84, v84, v84
	v_max_f32_e32 v78, 0, v79
	global_store_short v[82:83], v64, off offset:288
	v_cvt_pk_bf16_f32 v84, v84, s0
	v_mul_f32_e32 v78, v78, v78
	v_max_f32_e32 v64, 0, v67
	global_store_short v[94:95], v84, off offset:256
	v_cvt_pk_bf16_f32 v84, v78, s0
	v_add_co_u32_e32 v78, vcc, s27, v80
	v_mul_f32_e32 v64, v64, v64
	s_nop 0
	v_addc_co_u32_e32 v79, vcc, 0, v81, vcc
	v_cvt_pk_bf16_f32 v64, v64, s0
	global_store_short v[78:79], v64, off offset:288
	v_add_u32_e32 v64, 0x80, v136
	v_max_f32_e32 v68, 0, v68
	v_ashrrev_i32_e32 v65, 31, v64
	v_mul_f32_e32 v68, v68, v68
	v_lshlrev_b64 v[64:65], 13, v[64:65]
	v_max_f32_e32 v60, 0, v60
	v_cvt_pk_bf16_f32 v68, v68, s0
	v_lshl_add_u64 v[64:65], s[36:37], 0, v[64:65]
	v_mul_f32_e32 v60, v60, v60
	v_max_f32_e32 v48, 0, v48
	global_store_short v[80:81], v68, off offset:256
	v_lshl_add_u64 v[64:65], v[64:65], 0, v[138:139]
	v_cvt_pk_bf16_f32 v60, v60, s0
	v_mul_f32_e32 v48, v48, v48
	v_max_f32_e32 v68, 0, v69
	global_store_short v[64:65], v60, off
	v_cvt_pk_bf16_f32 v48, v48, s0
	v_mul_f32_e32 v68, v68, v68
	v_max_f32_e32 v60, 0, v61
	global_store_short v[64:65], v48, off offset:288
	v_cvt_pk_bf16_f32 v68, v68, s0
	v_mul_f32_e32 v60, v60, v60
	v_max_f32_e32 v48, 0, v49
	global_store_short v[76:77], v68, off offset:256
	v_cvt_pk_bf16_f32 v66, v60, s0
	v_add_co_u32_e32 v60, vcc, s3, v64
	v_mul_f32_e32 v48, v48, v48
	v_max_f32_e32 v68, 0, v70
	v_addc_co_u32_e32 v61, vcc, 0, v65, vcc
	v_cvt_pk_bf16_f32 v48, v48, s0
	v_mul_f32_e32 v68, v68, v68
	v_max_f32_e32 v62, 0, v62
	global_store_short v[60:61], v48, off offset:288
	v_cvt_pk_bf16_f32 v68, v68, s0
	global_store_short v[60:61], v66, off
	v_mul_f32_e32 v62, v62, v62
	v_add_co_u32_e32 v66, vcc, s25, v64
	v_max_f32_e32 v48, 0, v50
	global_store_short v[82:83], v68, off offset:256
	v_cvt_pk_bf16_f32 v62, v62, s0
	v_addc_co_u32_e32 v67, vcc, 0, v65, vcc
	v_mul_f32_e32 v48, v48, v48
	v_max_f32_e32 v68, 0, v71
	global_store_short v[66:67], v62, off
	v_cvt_pk_bf16_f32 v48, v48, s0
	v_mul_f32_e32 v68, v68, v68
	v_max_f32_e32 v62, 0, v63
	global_store_short v[66:67], v48, off offset:288
	v_cvt_pk_bf16_f32 v68, v68, s0
	v_mul_f32_e32 v62, v62, v62
	v_max_f32_e32 v48, 0, v51
	global_store_short v[78:79], v68, off offset:256
	v_cvt_pk_bf16_f32 v68, v62, s0
	v_add_co_u32_e32 v62, vcc, s27, v64
	v_mul_f32_e32 v48, v48, v48
	s_nop 0
	v_addc_co_u32_e32 v63, vcc, 0, v65, vcc
	v_cvt_pk_bf16_f32 v48, v48, s0
	global_store_short v[62:63], v48, off offset:288
	v_add_u32_e32 v48, 0x90, v136
	v_max_f32_e32 v52, 0, v52
	v_ashrrev_i32_e32 v49, 31, v48
	v_mul_f32_e32 v52, v52, v52
	v_lshlrev_b64 v[48:49], 13, v[48:49]
	v_max_f32_e32 v44, 0, v44
	v_cvt_pk_bf16_f32 v52, v52, s0
	v_lshl_add_u64 v[48:49], s[36:37], 0, v[48:49]
	v_mul_f32_e32 v44, v44, v44
	v_max_f32_e32 v32, 0, v32
	global_store_short v[64:65], v52, off offset:256
	v_lshl_add_u64 v[48:49], v[48:49], 0, v[138:139]
	v_cvt_pk_bf16_f32 v44, v44, s0
	v_mul_f32_e32 v32, v32, v32
	v_max_f32_e32 v52, 0, v53
	global_store_short v[48:49], v44, off
	v_cvt_pk_bf16_f32 v32, v32, s0
	v_mul_f32_e32 v52, v52, v52
	v_max_f32_e32 v44, 0, v45
	global_store_short v[48:49], v32, off offset:288
	v_cvt_pk_bf16_f32 v52, v52, s0
	v_mul_f32_e32 v44, v44, v44
	v_max_f32_e32 v32, 0, v33
	global_store_short v[60:61], v52, off offset:256
	v_cvt_pk_bf16_f32 v50, v44, s0
	v_add_co_u32_e32 v44, vcc, s3, v48
	v_mul_f32_e32 v32, v32, v32
	v_max_f32_e32 v52, 0, v54
	v_addc_co_u32_e32 v45, vcc, 0, v49, vcc
	v_cvt_pk_bf16_f32 v32, v32, s0
	v_mul_f32_e32 v52, v52, v52
	v_max_f32_e32 v46, 0, v46
	global_store_short v[44:45], v32, off offset:288
	v_cvt_pk_bf16_f32 v52, v52, s0
	global_store_short v[44:45], v50, off
	v_mul_f32_e32 v46, v46, v46
	v_add_co_u32_e32 v50, vcc, s25, v48
; DI bf16_t f2bf(float x) { return (bf16_t)(cvt_pk(x, 0.f) & 0xffffu); }
; DI float ex2(float x) { return __builtin_amdgcn_exp2f(x); }
;     ...
;     } else if (EPI == EPI_FFN1) {
;         bf16_t* d = (bf16_t*)(p.ws + OFF_U) + (size_t)row0 * 4096 + col;
; #pragma unroll
;         for (int e = 0; e < 4; ++e) { const float t = fmaxf(v[e], 0.f); d[(size_t)e * 4096] = f2bf(t * t); }
; template <int EPI, int K, int LNI = -1>
; DI void ph_gemm(const Params& p, const bf16_t* __restrict__ A, const bf16_t* __restrict__ Bt, int N, float* s_aux) {
;     ...
;             for (int ai = 0; ai < 2; ++ai)
; #pragma unroll
;                 for (int m = 0; m < 4; ++m) {
;                     const int lrow0 = ai * 128 + wr * 64 + m * 16 + fq * 4, row0 = brow + lrow0 + oz;
;                     f32x2 rs[4];
;                     if (EPI == EPI_RESID && LNI >= 0) {
;                         const f32x2* st_ = (const f32x2*)((unsigned char*)p.out + OFFO_STATS) + row0;
; #pragma unroll
;                         for (int e = 0; e < 4; ++e) rs[e] = st_[e];
;                     }
;                     if (EPI == EPI_E5) {
;                         const int idx_ = ((row0 % LT) + 48) & 63; const float lgh = lg_[0][0];
; #pragma unroll
;                         for (int e = 0; e < 4; ++e) rs[e] = (f32x2){ex2(lgh * (float)(idx_ + e + 1)), 0.0625f * ex2(lgh * (float)(63 - idx_ - e))};
;                     }
; #pragma unroll
;                     for (int bj = 0; bj < 2; ++bj)
; #pragma unroll
;                         for (int n = 0; n < 2; ++n) {
;                             float v[4];
; #pragma unroll
;                             for (int e = 0; e < 4; ++e) v[e] = acc[ai][bj][m][n][e];
;                             epi_store<EPI, LNI>(p, row0, bcol + bj * 128 + wc * 32 + n * 16 + fr + oz, lrow0, v, sa, rs, lg_[bj][n], lb_[bj][n]);
;                         }
	v_max_f32_e32 v32, 0, v34
	global_store_short v[66:67], v52, off offset:256
	v_cvt_pk_bf16_f32 v46, v46, s0
	v_addc_co_u32_e32 v51, vcc, 0, v49, vcc
	v_mul_f32_e32 v32, v32, v32
	v_max_f32_e32 v52, 0, v55
	global_store_short v[50:51], v46, off
	v_cvt_pk_bf16_f32 v32, v32, s0
	v_mul_f32_e32 v52, v52, v52
	v_max_f32_e32 v46, 0, v47
	global_store_short v[50:51], v32, off offset:288
	v_cvt_pk_bf16_f32 v52, v52, s0
	v_mul_f32_e32 v46, v46, v46
	v_max_f32_e32 v32, 0, v35
	global_store_short v[62:63], v52, off offset:256
	v_cvt_pk_bf16_f32 v52, v46, s0
	v_add_co_u32_e32 v46, vcc, s27, v48
	v_mul_f32_e32 v32, v32, v32
	s_nop 0
	v_addc_co_u32_e32 v47, vcc, 0, v49, vcc
	v_cvt_pk_bf16_f32 v32, v32, s0
	global_store_short v[46:47], v32, off offset:288
	v_add_u32_e32 v32, 0xa0, v136
	v_max_f32_e32 v36, 0, v36
	v_ashrrev_i32_e32 v33, 31, v32
	v_mul_f32_e32 v36, v36, v36
	v_lshlrev_b64 v[32:33], 13, v[32:33]
	v_max_f32_e32 v28, 0, v28
	v_cvt_pk_bf16_f32 v36, v36, s0
	v_lshl_add_u64 v[32:33], s[36:37], 0, v[32:33]
	v_mul_f32_e32 v28, v28, v28
	v_max_f32_e32 v16, 0, v16
	global_store_short v[48:49], v36, off offset:256
	v_lshl_add_u64 v[32:33], v[32:33], 0, v[138:139]
	v_cvt_pk_bf16_f32 v28, v28, s0
	v_mul_f32_e32 v16, v16, v16
	v_max_f32_e32 v36, 0, v37
	global_store_short v[32:33], v28, off
	v_cvt_pk_bf16_f32 v16, v16, s0
	v_mul_f32_e32 v36, v36, v36
	v_max_f32_e32 v28, 0, v29
	global_store_short v[32:33], v16, off offset:288
	v_cvt_pk_bf16_f32 v36, v36, s0
	v_mul_f32_e32 v28, v28, v28
	v_max_f32_e32 v16, 0, v17
	global_store_short v[44:45], v36, off offset:256
	v_cvt_pk_bf16_f32 v34, v28, s0
	v_add_co_u32_e32 v28, vcc, s3, v32
	v_mul_f32_e32 v16, v16, v16
	v_max_f32_e32 v36, 0, v38
	v_addc_co_u32_e32 v29, vcc, 0, v33, vcc
	v_cvt_pk_bf16_f32 v16, v16, s0
	v_mul_f32_e32 v36, v36, v36
	v_max_f32_e32 v30, 0, v30
	global_store_short v[28:29], v16, off offset:288
	v_cvt_pk_bf16_f32 v36, v36, s0
	global_store_short v[28:29], v34, off
	v_mul_f32_e32 v30, v30, v30
	v_add_co_u32_e32 v34, vcc, s25, v32
	v_max_f32_e32 v16, 0, v18
	global_store_short v[50:51], v36, off offset:256
	v_cvt_pk_bf16_f32 v30, v30, s0
	v_addc_co_u32_e32 v35, vcc, 0, v33, vcc
	v_mul_f32_e32 v16, v16, v16
	v_max_f32_e32 v36, 0, v39
	global_store_short v[34:35], v30, off
	v_cvt_pk_bf16_f32 v16, v16, s0
	v_mul_f32_e32 v36, v36, v36
	v_max_f32_e32 v30, 0, v31
	global_store_short v[34:35], v16, off offset:288
	v_cvt_pk_bf16_f32 v36, v36, s0
	v_mul_f32_e32 v30, v30, v30
	v_max_f32_e32 v16, 0, v19
	global_store_short v[46:47], v36, off offset:256
	v_cvt_pk_bf16_f32 v36, v30, s0
	v_add_co_u32_e32 v30, vcc, s27, v32
	v_mul_f32_e32 v16, v16, v16
	s_nop 0
	v_addc_co_u32_e32 v31, vcc, 0, v33, vcc
	v_cvt_pk_bf16_f32 v16, v16, s0
	v_max_f32_e32 v20, 0, v20
	global_store_short v[30:31], v16, off offset:288
	v_add_u32_e32 v16, 0xb0, v136
	v_mul_f32_e32 v20, v20, v20
	v_ashrrev_i32_e32 v17, 31, v16
	v_cvt_pk_bf16_f32 v20, v20, s0
	v_lshlrev_b64 v[16:17], 13, v[16:17]
	v_max_f32_e32 v12, 0, v12
	v_max_f32_e32 v120, 0, v120
	v_max_f32_e32 v104, 0, v104
	v_max_f32_e32 v88, 0, v88
	v_max_f32_e32 v72, 0, v72
	v_max_f32_e32 v56, 0, v56
	v_max_f32_e32 v40, 0, v40
	v_max_f32_e32 v24, 0, v24
	global_store_short v[32:33], v20, off offset:256
	v_lshl_add_u64 v[16:17], s[36:37], 0, v[16:17]
	v_mul_f32_e32 v12, v12, v12
	v_max_f32_e32 v8, 0, v8
	v_max_f32_e32 v4, 0, v4
	v_max_f32_e32 v0, 0, v0
	v_mul_f32_e32 v120, v120, v120
	v_mul_f32_e32 v104, v104, v104
	v_mul_f32_e32 v88, v88, v88
	v_mul_f32_e32 v72, v72, v72
	v_mul_f32_e32 v56, v56, v56
	v_mul_f32_e32 v40, v40, v40
	v_mul_f32_e32 v24, v24, v24
	v_max_f32_e32 v20, 0, v21
	v_lshl_add_u64 v[16:17], v[16:17], 0, v[138:139]
	v_cvt_pk_bf16_f32 v12, v12, s0
	v_mul_f32_e32 v8, v8, v8
	v_mul_f32_e32 v4, v4, v4
	v_mul_f32_e32 v0, v0, v0
	v_cvt_pk_bf16_f32 v120, v120, s0
	v_cvt_pk_bf16_f32 v104, v104, s0
	v_cvt_pk_bf16_f32 v88, v88, s0
	v_cvt_pk_bf16_f32 v72, v72, s0
	v_cvt_pk_bf16_f32 v56, v56, s0
	v_cvt_pk_bf16_f32 v40, v40, s0
	v_cvt_pk_bf16_f32 v24, v24, s0
	v_mul_f32_e32 v20, v20, v20
	global_store_short v[16:17], v12, off
	v_cvt_pk_bf16_f32 v8, v8, s0
	v_cvt_pk_bf16_f32 v4, v4, s0
	v_cvt_pk_bf16_f32 v0, v0, s0
	global_store_short v[166:167], v120, off offset:32
	global_store_short v[112:113], v104, off offset:32
	global_store_short v[96:97], v88, off offset:32
	global_store_short v[80:81], v72, off offset:32
	global_store_short v[64:65], v56, off offset:32
	global_store_short v[48:49], v40, off offset:32
	global_store_short v[32:33], v24, off offset:32
	v_cvt_pk_bf16_f32 v20, v20, s0
	v_max_f32_e32 v12, 0, v13
	global_store_short v[16:17], v8, off offset:32
	global_store_short v[16:17], v4, off offset:256
	global_store_short v[16:17], v0, off offset:288
	v_max_f32_e32 v120, 0, v121
	v_max_f32_e32 v104, 0, v105
	v_max_f32_e32 v88, 0, v89
	v_max_f32_e32 v72, 0, v73
	v_max_f32_e32 v56, 0, v57
	v_max_f32_e32 v40, 0, v41
	v_max_f32_e32 v24, 0, v25
	global_store_short v[28:29], v20, off offset:256
	v_mul_f32_e32 v12, v12, v12
	v_max_f32_e32 v8, 0, v9
	v_max_f32_e32 v4, 0, v5
	v_max_f32_e32 v0, 0, v1
	v_mul_f32_e32 v120, v120, v120
	v_mul_f32_e32 v104, v104, v104
; DI bf16_t f2bf(float x) { return (bf16_t)(cvt_pk(x, 0.f) & 0xffffu); }
; DI float ex2(float x) { return __builtin_amdgcn_exp2f(x); }
; #define BAR __builtin_amdgcn_s_barrier()
;     ...
;     } else if (EPI == EPI_FFN1) {
;         bf16_t* d = (bf16_t*)(p.ws + OFF_U) + (size_t)row0 * 4096 + col;
; #pragma unroll
;         for (int e = 0; e < 4; ++e) { const float t = fmaxf(v[e], 0.f); d[(size_t)e * 4096] = f2bf(t * t); }
; template <int EPI, int K, int LNI = -1>
; DI void ph_gemm(const Params& p, const bf16_t* __restrict__ A, const bf16_t* __restrict__ Bt, int N, float* s_aux) {
;     ...
;             for (int ai = 0; ai < 2; ++ai)
; #pragma unroll
;                 for (int m = 0; m < 4; ++m) {
;                     const int lrow0 = ai * 128 + wr * 64 + m * 16 + fq * 4, row0 = brow + lrow0 + oz;
;                     f32x2 rs[4];
;                     if (EPI == EPI_RESID && LNI >= 0) {
;                         const f32x2* st_ = (const f32x2*)((unsigned char*)p.out + OFFO_STATS) + row0;
; #pragma unroll
;                         for (int e = 0; e < 4; ++e) rs[e] = st_[e];
;                     }
;                     if (EPI == EPI_E5) {
;                         const int idx_ = ((row0 % LT) + 48) & 63; const float lgh = lg_[0][0];
; #pragma unroll
;                         for (int e = 0; e < 4; ++e) rs[e] = (f32x2){ex2(lgh * (float)(idx_ + e + 1)), 0.0625f * ex2(lgh * (float)(63 - idx_ - e))};
;                     }
; #pragma unroll
;                     for (int bj = 0; bj < 2; ++bj)
; #pragma unroll
;                         for (int n = 0; n < 2; ++n) {
;                             float v[4];
; #pragma unroll
;                             for (int e = 0; e < 4; ++e) v[e] = acc[ai][bj][m][n][e];
;                             epi_store<EPI, LNI>(p, row0, bcol + bj * 128 + wc * 32 + n * 16 + fr + oz, lrow0, v, sa, rs, lg_[bj][n], lb_[bj][n]);
;                         }
;                 }
;         }
;         if (!has_next) break;
; #pragma unroll
;         for (int a = 0; a < 2; ++a)
; #pragma unroll
;             for (int b = 0; b < 2; ++b)
; #pragma unroll
;                 for (int m = 0; m < 4; ++m)
; #pragma unroll
;                     for (int n = 0; n < 2; ++n) acc[a][b][m][n] = (f32x4){0.f, 0.f, 0.f, 0.f};
;         pm = npm; pn = npn; cA = nA; cB = nB; it = itn; ++cnt;
;         if (wr == 1) BAR;
;     }
	v_mul_f32_e32 v88, v88, v88
	v_mul_f32_e32 v72, v72, v72
	v_mul_f32_e32 v56, v56, v56
	v_mul_f32_e32 v40, v40, v40
	v_mul_f32_e32 v24, v24, v24
	v_max_f32_e32 v20, 0, v22
	v_cvt_pk_bf16_f32 v18, v12, s0
	v_add_co_u32_e32 v12, vcc, s3, v16
	s_nop 1
	v_mul_f32_e32 v8, v8, v8
	v_mul_f32_e32 v4, v4, v4
	v_mul_f32_e32 v0, v0, v0
	v_cvt_pk_bf16_f32 v120, v120, s0
	v_cvt_pk_bf16_f32 v104, v104, s0
	v_cvt_pk_bf16_f32 v88, v88, s0
	v_cvt_pk_bf16_f32 v72, v72, s0
	v_cvt_pk_bf16_f32 v56, v56, s0
	v_cvt_pk_bf16_f32 v40, v40, s0
	v_cvt_pk_bf16_f32 v24, v24, s0
	v_mul_f32_e32 v20, v20, v20
	v_addc_co_u32_e32 v13, vcc, 0, v17, vcc
	v_max_f32_e32 v14, 0, v14
	v_cvt_pk_bf16_f32 v8, v8, s0
	v_cvt_pk_bf16_f32 v4, v4, s0
	v_cvt_pk_bf16_f32 v0, v0, s0
	global_store_short v[124:125], v120, off offset:32
	global_store_short v[108:109], v104, off offset:32
	global_store_short v[92:93], v88, off offset:32
	global_store_short v[76:77], v72, off offset:32
	global_store_short v[60:61], v56, off offset:32
	global_store_short v[44:45], v40, off offset:32
	global_store_short v[28:29], v24, off offset:32
	v_cvt_pk_bf16_f32 v20, v20, s0
	global_store_short v[12:13], v18, off
	v_mul_f32_e32 v14, v14, v14
	v_add_co_u32_e32 v18, vcc, s25, v16
	global_store_short v[12:13], v8, off offset:32
	global_store_short v[12:13], v4, off offset:256
	global_store_short v[12:13], v0, off offset:288
	v_max_f32_e32 v120, 0, v122
	v_max_f32_e32 v104, 0, v106
	v_max_f32_e32 v88, 0, v90
	v_max_f32_e32 v72, 0, v74
	v_max_f32_e32 v56, 0, v58
	v_max_f32_e32 v40, 0, v42
	v_max_f32_e32 v24, 0, v26
	global_store_short v[34:35], v20, off offset:256
	v_cvt_pk_bf16_f32 v14, v14, s0
	v_addc_co_u32_e32 v19, vcc, 0, v17, vcc
	v_max_f32_e32 v8, 0, v10
	v_max_f32_e32 v4, 0, v6
	v_max_f32_e32 v0, 0, v2
	v_mul_f32_e32 v120, v120, v120
	v_mul_f32_e32 v104, v104, v104
	v_mul_f32_e32 v88, v88, v88
	v_mul_f32_e32 v72, v72, v72
	v_mul_f32_e32 v56, v56, v56
	v_mul_f32_e32 v40, v40, v40
	v_mul_f32_e32 v24, v24, v24
	v_max_f32_e32 v20, 0, v23
	global_store_short v[18:19], v14, off
	v_mul_f32_e32 v8, v8, v8
	v_mul_f32_e32 v4, v4, v4
	v_mul_f32_e32 v0, v0, v0
	v_cvt_pk_bf16_f32 v120, v120, s0
	v_cvt_pk_bf16_f32 v104, v104, s0
	v_cvt_pk_bf16_f32 v88, v88, s0
	v_cvt_pk_bf16_f32 v72, v72, s0
	v_cvt_pk_bf16_f32 v56, v56, s0
	v_cvt_pk_bf16_f32 v40, v40, s0
	v_cvt_pk_bf16_f32 v24, v24, s0
	v_mul_f32_e32 v20, v20, v20
	v_max_f32_e32 v14, 0, v15
	v_cvt_pk_bf16_f32 v8, v8, s0
	v_cvt_pk_bf16_f32 v4, v4, s0
	v_cvt_pk_bf16_f32 v0, v0, s0
	global_store_short v[168:169], v120, off offset:32
	global_store_short v[114:115], v104, off offset:32
	global_store_short v[98:99], v88, off offset:32
	global_store_short v[82:83], v72, off offset:32
	global_store_short v[66:67], v56, off offset:32
	global_store_short v[50:51], v40, off offset:32
	global_store_short v[34:35], v24, off offset:32
	v_cvt_pk_bf16_f32 v20, v20, s0
	v_mul_f32_e32 v14, v14, v14
	global_store_short v[18:19], v8, off offset:32
	global_store_short v[18:19], v4, off offset:256
	global_store_short v[18:19], v0, off offset:288
	v_max_f32_e32 v120, 0, v123
	v_max_f32_e32 v104, 0, v107
	v_max_f32_e32 v88, 0, v91
	v_max_f32_e32 v72, 0, v75
	v_max_f32_e32 v56, 0, v59
	v_max_f32_e32 v40, 0, v43
	v_max_f32_e32 v24, 0, v27
	global_store_short v[30:31], v20, off offset:256
	v_cvt_pk_bf16_f32 v20, v14, s0
	v_add_co_u32_e32 v14, vcc, s27, v16
	v_max_f32_e32 v8, 0, v11
	v_max_f32_e32 v4, 0, v7
	v_max_f32_e32 v0, 0, v3
	v_mul_f32_e32 v120, v120, v120
	v_mul_f32_e32 v104, v104, v104
	v_mul_f32_e32 v88, v88, v88
	v_mul_f32_e32 v72, v72, v72
	v_mul_f32_e32 v56, v56, v56
	v_mul_f32_e32 v40, v40, v40
	v_mul_f32_e32 v24, v24, v24
	v_addc_co_u32_e32 v15, vcc, 0, v17, vcc
	v_mul_f32_e32 v8, v8, v8
	v_mul_f32_e32 v4, v4, v4
	v_mul_f32_e32 v0, v0, v0
	v_cvt_pk_bf16_f32 v120, v120, s0
	v_cvt_pk_bf16_f32 v104, v104, s0
	v_cvt_pk_bf16_f32 v88, v88, s0
	v_cvt_pk_bf16_f32 v72, v72, s0
	v_cvt_pk_bf16_f32 v56, v56, s0
	v_cvt_pk_bf16_f32 v40, v40, s0
	v_cvt_pk_bf16_f32 v24, v24, s0
	v_cvt_pk_bf16_f32 v8, v8, s0
	v_cvt_pk_bf16_f32 v4, v4, s0
	v_cvt_pk_bf16_f32 v0, v0, s0
	s_andn2_b64 vcc, exec, s[12:13]
	s_mov_b64 s[12:13], -1
	global_store_short v[126:127], v137, off
	global_store_short v[126:127], v120, off offset:32
	global_store_short v[110:111], v116, off
	global_store_short v[110:111], v104, off offset:32
	global_store_short v[94:95], v100, off
	global_store_short v[94:95], v88, off offset:32
	global_store_short v[78:79], v84, off
	global_store_short v[78:79], v72, off offset:32
	global_store_short v[62:63], v68, off
	global_store_short v[62:63], v56, off offset:32
	global_store_short v[46:47], v52, off
	global_store_short v[46:47], v40, off offset:32
	global_store_short v[30:31], v36, off
	global_store_short v[30:31], v24, off offset:32
	global_store_short v[14:15], v20, off
	global_store_short v[14:15], v8, off offset:32
	global_store_short v[14:15], v4, off offset:256
	global_store_short v[14:15], v0, off offset:288
	s_cbranch_vccnz .LBB0_920
	s_and_saveexec_b64 s[12:13], s[0:1]
	s_xor_b64 s[12:13], exec, s[12:13]
	s_cbranch_execz .LBB0_919
	s_barrier
	s_branch .LBB0_919

; DI bf16_t f2bf(float x) { return (bf16_t)(cvt_pk(x, 0.f) & 0xffffu); }
; DI float ex2(float x) { return __builtin_amdgcn_exp2f(x); }
;     ...
;     } else if (EPI == EPI_FFN1) {
;         bf16_t* d = (bf16_t*)(p.ws + OFF_U) + (size_t)row0 * 4096 + col;
; #pragma unroll
;         for (int e = 0; e < 4; ++e) { const float t = fmaxf(v[e], 0.f); d[(size_t)e * 4096] = f2bf(t * t); }
; template <int EPI, int K, int LNI = -1>
; DI void ph_gemm(const Params& p, const bf16_t* __restrict__ A, const bf16_t* __restrict__ Bt, int N, float* s_aux) {
;     ...
;             for (int ai = 0; ai < 2; ++ai)
; #pragma unroll
;                 for (int m = 0; m < 4; ++m) {
;                     const int lrow0 = ai * 128 + wr * 64 + m * 16 + fq * 4, row0 = brow + lrow0 + oz;
;                     f32x2 rs[4];
;                     if (EPI == EPI_RESID && LNI >= 0) {
;                         const f32x2* st_ = (const f32x2*)((unsigned char*)p.out + OFFO_STATS) + row0;
; #pragma unroll
;                         for (int e = 0; e < 4; ++e) rs[e] = st_[e];
;                     }
;                     if (EPI == EPI_E5) {
;                         const int idx_ = ((row0 % LT) + 48) & 63; const float lgh = lg_[0][0];
; #pragma unroll
;                         for (int e = 0; e < 4; ++e) rs[e] = (f32x2){ex2(lgh * (float)(idx_ + e + 1)), 0.0625f * ex2(lgh * (float)(63 - idx_ - e))};
;                     }
; #pragma unroll
;                     for (int bj = 0; bj < 2; ++bj)
; #pragma unroll
;                         for (int n = 0; n < 2; ++n) {
;                             float v[4];
; #pragma unroll
;                             for (int e = 0; e < 4; ++e) v[e] = acc[ai][bj][m][n][e];
;                             epi_store<EPI, LNI>(p, row0, bcol + bj * 128 + wc * 32 + n * 16 + fr + oz, lrow0, v, sa, rs, lg_[bj][n], lb_[bj][n]);
;                         }
.LBB0_1856:
	s_or_b64 exec, exec, s[44:45]
	s_lshl_b32 s21, s42, 8
	v_mov_b32_e32 v137, 0
	v_lshl_or_b32 v138, s28, 8, v155
	v_add3_u32 v136, v154, s21, v137
	v_add_u32_e32 v138, v138, v137
	v_ashrrev_i32_e32 v137, 31, v136
	v_lshlrev_b64 v[166:167], 13, v[136:137]
	v_ashrrev_i32_e32 v139, 31, v138
	v_max_f32_e32 v124, 0, v124
	v_lshl_add_u64 v[166:167], s[36:37], 0, v[166:167]
	v_lshlrev_b64 v[138:139], 1, v[138:139]
	v_mul_f32_e32 v124, v124, v124
	v_max_f32_e32 v112, 0, v112
	v_lshl_add_u64 v[166:167], v[166:167], 0, v[138:139]
	v_cvt_pk_bf16_f32 v124, v124, s0
	v_mul_f32_e32 v112, v112, v112
	global_store_short v[166:167], v124, off
	v_cvt_pk_bf16_f32 v112, v112, s0
	v_max_f32_e32 v124, 0, v125
	global_store_short v[166:167], v112, off offset:288
	v_mul_f32_e32 v124, v124, v124
	v_max_f32_e32 v112, 0, v113
	v_cvt_pk_bf16_f32 v137, v124, s0
	v_add_co_u32_e32 v124, vcc, s3, v166
	v_mul_f32_e32 v112, v112, v112
	s_nop 0
	v_addc_co_u32_e32 v125, vcc, 0, v167, vcc
	v_cvt_pk_bf16_f32 v112, v112, s0
	v_max_f32_e32 v126, 0, v126
	global_store_short v[124:125], v112, off offset:288
	v_mul_f32_e32 v126, v126, v126
	v_add_co_u32_e32 v168, vcc, s29, v166
	v_max_f32_e32 v112, 0, v114
	v_cvt_pk_bf16_f32 v126, v126, s0
	v_addc_co_u32_e32 v169, vcc, 0, v167, vcc
	v_mul_f32_e32 v112, v112, v112
	global_store_short v[168:169], v126, off
	v_cvt_pk_bf16_f32 v112, v112, s0
	v_max_f32_e32 v126, 0, v127
	global_store_short v[168:169], v112, off offset:288
	v_mul_f32_e32 v126, v126, v126
	v_max_f32_e32 v112, 0, v115
	global_store_short v[124:125], v137, off
	v_cvt_pk_bf16_f32 v137, v126, s0
	v_add_co_u32_e32 v126, vcc, s35, v166
	v_mul_f32_e32 v112, v112, v112
	s_nop 0
	v_addc_co_u32_e32 v127, vcc, 0, v167, vcc
	v_cvt_pk_bf16_f32 v112, v112, s0
	global_store_short v[126:127], v112, off offset:288
	v_add_u32_e32 v112, 16, v136
	v_max_f32_e32 v116, 0, v116
	v_ashrrev_i32_e32 v113, 31, v112
	v_mul_f32_e32 v116, v116, v116
	v_lshlrev_b64 v[112:113], 13, v[112:113]
	v_max_f32_e32 v108, 0, v108
	v_cvt_pk_bf16_f32 v116, v116, s0
	v_lshl_add_u64 v[112:113], s[36:37], 0, v[112:113]
	v_mul_f32_e32 v108, v108, v108
	v_max_f32_e32 v96, 0, v96
	global_store_short v[166:167], v116, off offset:256
	v_lshl_add_u64 v[112:113], v[112:113], 0, v[138:139]
	v_cvt_pk_bf16_f32 v108, v108, s0
	v_mul_f32_e32 v96, v96, v96
	v_max_f32_e32 v116, 0, v117
	global_store_short v[112:113], v108, off
	v_cvt_pk_bf16_f32 v96, v96, s0
	v_mul_f32_e32 v116, v116, v116
	v_max_f32_e32 v108, 0, v109
	global_store_short v[112:113], v96, off offset:288
	v_cvt_pk_bf16_f32 v116, v116, s0
	v_mul_f32_e32 v108, v108, v108
	v_max_f32_e32 v96, 0, v97
	global_store_short v[124:125], v116, off offset:256
	v_cvt_pk_bf16_f32 v114, v108, s0
	v_add_co_u32_e32 v108, vcc, s3, v112
	v_mul_f32_e32 v96, v96, v96
	v_max_f32_e32 v116, 0, v118
	v_addc_co_u32_e32 v109, vcc, 0, v113, vcc
	v_cvt_pk_bf16_f32 v96, v96, s0
	v_mul_f32_e32 v116, v116, v116
	v_max_f32_e32 v110, 0, v110
	global_store_short v[108:109], v96, off offset:288
	v_cvt_pk_bf16_f32 v116, v116, s0
	global_store_short v[108:109], v114, off
	v_mul_f32_e32 v110, v110, v110
	v_add_co_u32_e32 v114, vcc, s29, v112
	v_max_f32_e32 v96, 0, v98
	global_store_short v[168:169], v116, off offset:256
	v_cvt_pk_bf16_f32 v110, v110, s0
	v_addc_co_u32_e32 v115, vcc, 0, v113, vcc
	v_mul_f32_e32 v96, v96, v96
	v_max_f32_e32 v116, 0, v119
	global_store_short v[114:115], v110, off
	v_cvt_pk_bf16_f32 v96, v96, s0
	v_mul_f32_e32 v116, v116, v116
	v_max_f32_e32 v110, 0, v111
	global_store_short v[114:115], v96, off offset:288
	v_cvt_pk_bf16_f32 v116, v116, s0
	v_mul_f32_e32 v110, v110, v110
	v_max_f32_e32 v96, 0, v99
	global_store_short v[126:127], v116, off offset:256
	v_cvt_pk_bf16_f32 v116, v110, s0
	v_add_co_u32_e32 v110, vcc, s35, v112
	v_mul_f32_e32 v96, v96, v96
	s_nop 0
	v_addc_co_u32_e32 v111, vcc, 0, v113, vcc
	v_cvt_pk_bf16_f32 v96, v96, s0
	global_store_short v[110:111], v96, off offset:288
	v_add_u32_e32 v96, 32, v136
	v_max_f32_e32 v100, 0, v100
	v_ashrrev_i32_e32 v97, 31, v96
	v_mul_f32_e32 v100, v100, v100
	v_lshlrev_b64 v[96:97], 13, v[96:97]
	v_max_f32_e32 v92, 0, v92
	v_cvt_pk_bf16_f32 v100, v100, s0
	v_lshl_add_u64 v[96:97], s[36:37], 0, v[96:97]
	v_mul_f32_e32 v92, v92, v92
	v_max_f32_e32 v80, 0, v80
	global_store_short v[112:113], v100, off offset:256
	v_lshl_add_u64 v[96:97], v[96:97], 0, v[138:139]
	v_cvt_pk_bf16_f32 v92, v92, s0
	v_mul_f32_e32 v80, v80, v80
	v_max_f32_e32 v100, 0, v101
	global_store_short v[96:97], v92, off
	v_cvt_pk_bf16_f32 v80, v80, s0
	v_mul_f32_e32 v100, v100, v100
	v_max_f32_e32 v92, 0, v93
	global_store_short v[96:97], v80, off offset:288
	v_cvt_pk_bf16_f32 v100, v100, s0
	v_mul_f32_e32 v92, v92, v92
	v_max_f32_e32 v80, 0, v81
	global_store_short v[108:109], v100, off offset:256
	v_cvt_pk_bf16_f32 v98, v92, s0
	v_add_co_u32_e32 v92, vcc, s3, v96
	v_mul_f32_e32 v80, v80, v80
	v_max_f32_e32 v100, 0, v102
	v_addc_co_u32_e32 v93, vcc, 0, v97, vcc
	v_cvt_pk_bf16_f32 v80, v80, s0
	v_mul_f32_e32 v100, v100, v100
	v_max_f32_e32 v94, 0, v94
	global_store_short v[92:93], v80, off offset:288
	v_cvt_pk_bf16_f32 v100, v100, s0
	global_store_short v[92:93], v98, off
	v_mul_f32_e32 v94, v94, v94
	v_add_co_u32_e32 v98, vcc, s29, v96
	v_max_f32_e32 v80, 0, v82
	global_store_short v[114:115], v100, off offset:256
	v_cvt_pk_bf16_f32 v94, v94, s0
	v_addc_co_u32_e32 v99, vcc, 0, v97, vcc
	v_mul_f32_e32 v80, v80, v80
	v_max_f32_e32 v100, 0, v103
	global_store_short v[98:99], v94, off
	v_cvt_pk_bf16_f32 v80, v80, s0
	v_mul_f32_e32 v100, v100, v100
	v_max_f32_e32 v94, 0, v95
	global_store_short v[98:99], v80, off offset:288
	v_cvt_pk_bf16_f32 v100, v100, s0
; DI bf16_t f2bf(float x) { return (bf16_t)(cvt_pk(x, 0.f) & 0xffffu); }
; DI float ex2(float x) { return __builtin_amdgcn_exp2f(x); }
;     ...
;     } else if (EPI == EPI_FFN1) {
;         bf16_t* d = (bf16_t*)(p.ws + OFF_U) + (size_t)row0 * 4096 + col;
; #pragma unroll
;         for (int e = 0; e < 4; ++e) { const float t = fmaxf(v[e], 0.f); d[(size_t)e * 4096] = f2bf(t * t); }
; template <int EPI, int K, int LNI = -1>
; DI void ph_gemm(const Params& p, const bf16_t* __restrict__ A, const bf16_t* __restrict__ Bt, int N, float* s_aux) {
;     ...
;             for (int ai = 0; ai < 2; ++ai)
; #pragma unroll
;                 for (int m = 0; m < 4; ++m) {
;                     const int lrow0 = ai * 128 + wr * 64 + m * 16 + fq * 4, row0 = brow + lrow0 + oz;
;                     f32x2 rs[4];
;                     if (EPI == EPI_RESID && LNI >= 0) {
;                         const f32x2* st_ = (const f32x2*)((unsigned char*)p.out + OFFO_STATS) + row0;
; #pragma unroll
;                         for (int e = 0; e < 4; ++e) rs[e] = st_[e];
;                     }
;                     if (EPI == EPI_E5) {
;                         const int idx_ = ((row0 % LT) + 48) & 63; const float lgh = lg_[0][0];
; #pragma unroll
;                         for (int e = 0; e < 4; ++e) rs[e] = (f32x2){ex2(lgh * (float)(idx_ + e + 1)), 0.0625f * ex2(lgh * (float)(63 - idx_ - e))};
;                     }
; #pragma unroll
;                     for (int bj = 0; bj < 2; ++bj)
; #pragma unroll
;                         for (int n = 0; n < 2; ++n) {
;                             float v[4];
; #pragma unroll
;                             for (int e = 0; e < 4; ++e) v[e] = acc[ai][bj][m][n][e];
;                             epi_store<EPI, LNI>(p, row0, bcol + bj * 128 + wc * 32 + n * 16 + fr + oz, lrow0, v, sa, rs, lg_[bj][n], lb_[bj][n]);
;                         }
	v_mul_f32_e32 v94, v94, v94
	v_max_f32_e32 v80, 0, v83
	global_store_short v[110:111], v100, off offset:256
	v_cvt_pk_bf16_f32 v100, v94, s0
	v_add_co_u32_e32 v94, vcc, s35, v96
	v_mul_f32_e32 v80, v80, v80
	s_nop 0
	v_addc_co_u32_e32 v95, vcc, 0, v97, vcc
	v_cvt_pk_bf16_f32 v80, v80, s0
	global_store_short v[94:95], v80, off offset:288
	v_add_u32_e32 v80, 48, v136
	v_max_f32_e32 v84, 0, v84
	v_ashrrev_i32_e32 v81, 31, v80
	v_mul_f32_e32 v84, v84, v84
	v_lshlrev_b64 v[80:81], 13, v[80:81]
	v_max_f32_e32 v76, 0, v76
	v_cvt_pk_bf16_f32 v84, v84, s0
	v_lshl_add_u64 v[80:81], s[36:37], 0, v[80:81]
	v_mul_f32_e32 v76, v76, v76
	v_max_f32_e32 v64, 0, v64
	global_store_short v[96:97], v84, off offset:256
	v_lshl_add_u64 v[80:81], v[80:81], 0, v[138:139]
	v_cvt_pk_bf16_f32 v76, v76, s0
	v_mul_f32_e32 v64, v64, v64
	v_max_f32_e32 v84, 0, v85
	global_store_short v[80:81], v76, off
	v_cvt_pk_bf16_f32 v64, v64, s0
	v_mul_f32_e32 v84, v84, v84
	v_max_f32_e32 v76, 0, v77
	global_store_short v[80:81], v64, off offset:288
	v_cvt_pk_bf16_f32 v84, v84, s0
	v_mul_f32_e32 v76, v76, v76
	v_max_f32_e32 v64, 0, v65
	global_store_short v[92:93], v84, off offset:256
	v_cvt_pk_bf16_f32 v82, v76, s0
	v_add_co_u32_e32 v76, vcc, s3, v80
	v_mul_f32_e32 v64, v64, v64
	v_max_f32_e32 v84, 0, v86
	v_addc_co_u32_e32 v77, vcc, 0, v81, vcc
	v_cvt_pk_bf16_f32 v64, v64, s0
	v_mul_f32_e32 v84, v84, v84
	v_max_f32_e32 v78, 0, v78
	global_store_short v[76:77], v64, off offset:288
	v_cvt_pk_bf16_f32 v84, v84, s0
	global_store_short v[76:77], v82, off
	v_mul_f32_e32 v78, v78, v78
	v_add_co_u32_e32 v82, vcc, s29, v80
	v_max_f32_e32 v64, 0, v66
	global_store_short v[98:99], v84, off offset:256
	v_cvt_pk_bf16_f32 v78, v78, s0
	v_addc_co_u32_e32 v83, vcc, 0, v81, vcc
	v_mul_f32_e32 v64, v64, v64
	v_max_f32_e32 v84, 0, v87
	global_store_short v[82:83], v78, off
	v_cvt_pk_bf16_f32 v64, v64, s0
	v_mul_f32_e32 v84, v84, v84
	v_max_f32_e32 v78, 0, v79
	global_store_short v[82:83], v64, off offset:288
	v_cvt_pk_bf16_f32 v84, v84, s0
	v_mul_f32_e32 v78, v78, v78
	v_max_f32_e32 v64, 0, v67
	global_store_short v[94:95], v84, off offset:256
	v_cvt_pk_bf16_f32 v84, v78, s0
	v_add_co_u32_e32 v78, vcc, s35, v80
	v_mul_f32_e32 v64, v64, v64
	s_nop 0
	v_addc_co_u32_e32 v79, vcc, 0, v81, vcc
	v_cvt_pk_bf16_f32 v64, v64, s0
	global_store_short v[78:79], v64, off offset:288
	v_add_u32_e32 v64, 0x80, v136
	v_max_f32_e32 v68, 0, v68
	v_ashrrev_i32_e32 v65, 31, v64
	v_mul_f32_e32 v68, v68, v68
	v_lshlrev_b64 v[64:65], 13, v[64:65]
	v_max_f32_e32 v60, 0, v60
	v_cvt_pk_bf16_f32 v68, v68, s0
	v_lshl_add_u64 v[64:65], s[36:37], 0, v[64:65]
	v_mul_f32_e32 v60, v60, v60
	v_max_f32_e32 v48, 0, v48
	global_store_short v[80:81], v68, off offset:256
	v_lshl_add_u64 v[64:65], v[64:65], 0, v[138:139]
	v_cvt_pk_bf16_f32 v60, v60, s0
	v_mul_f32_e32 v48, v48, v48
	v_max_f32_e32 v68, 0, v69
	global_store_short v[64:65], v60, off
	v_cvt_pk_bf16_f32 v48, v48, s0
	v_mul_f32_e32 v68, v68, v68
	v_max_f32_e32 v60, 0, v61
	global_store_short v[64:65], v48, off offset:288
	v_cvt_pk_bf16_f32 v68, v68, s0
	v_mul_f32_e32 v60, v60, v60
	v_max_f32_e32 v48, 0, v49
	global_store_short v[76:77], v68, off offset:256
	v_cvt_pk_bf16_f32 v66, v60, s0
	v_add_co_u32_e32 v60, vcc, s3, v64
	v_mul_f32_e32 v48, v48, v48
	v_max_f32_e32 v68, 0, v70
	v_addc_co_u32_e32 v61, vcc, 0, v65, vcc
	v_cvt_pk_bf16_f32 v48, v48, s0
	v_mul_f32_e32 v68, v68, v68
	v_max_f32_e32 v62, 0, v62
	global_store_short v[60:61], v48, off offset:288
	v_cvt_pk_bf16_f32 v68, v68, s0
	global_store_short v[60:61], v66, off
	v_mul_f32_e32 v62, v62, v62
	v_add_co_u32_e32 v66, vcc, s29, v64
	v_max_f32_e32 v48, 0, v50
	global_store_short v[82:83], v68, off offset:256
	v_cvt_pk_bf16_f32 v62, v62, s0
	v_addc_co_u32_e32 v67, vcc, 0, v65, vcc
	v_mul_f32_e32 v48, v48, v48
	v_max_f32_e32 v68, 0, v71
	global_store_short v[66:67], v62, off
	v_cvt_pk_bf16_f32 v48, v48, s0
	v_mul_f32_e32 v68, v68, v68
	v_max_f32_e32 v62, 0, v63
	global_store_short v[66:67], v48, off offset:288
	v_cvt_pk_bf16_f32 v68, v68, s0
	v_mul_f32_e32 v62, v62, v62
	v_max_f32_e32 v48, 0, v51
	global_store_short v[78:79], v68, off offset:256
	v_cvt_pk_bf16_f32 v68, v62, s0
	v_add_co_u32_e32 v62, vcc, s35, v64
	v_mul_f32_e32 v48, v48, v48
	s_nop 0
	v_addc_co_u32_e32 v63, vcc, 0, v65, vcc
	v_cvt_pk_bf16_f32 v48, v48, s0
	global_store_short v[62:63], v48, off offset:288
	v_add_u32_e32 v48, 0x90, v136
	v_max_f32_e32 v52, 0, v52
	v_ashrrev_i32_e32 v49, 31, v48
	v_mul_f32_e32 v52, v52, v52
	v_lshlrev_b64 v[48:49], 13, v[48:49]
	v_max_f32_e32 v44, 0, v44
	v_cvt_pk_bf16_f32 v52, v52, s0
	v_lshl_add_u64 v[48:49], s[36:37], 0, v[48:49]
	v_mul_f32_e32 v44, v44, v44
	v_max_f32_e32 v32, 0, v32
	global_store_short v[64:65], v52, off offset:256
	v_lshl_add_u64 v[48:49], v[48:49], 0, v[138:139]
	v_cvt_pk_bf16_f32 v44, v44, s0
	v_mul_f32_e32 v32, v32, v32
	v_max_f32_e32 v52, 0, v53
	global_store_short v[48:49], v44, off
	v_cvt_pk_bf16_f32 v32, v32, s0
	v_mul_f32_e32 v52, v52, v52
	v_max_f32_e32 v44, 0, v45
	global_store_short v[48:49], v32, off offset:288
	v_cvt_pk_bf16_f32 v52, v52, s0
	v_mul_f32_e32 v44, v44, v44
	v_max_f32_e32 v32, 0, v33
	global_store_short v[60:61], v52, off offset:256
	v_cvt_pk_bf16_f32 v50, v44, s0
	v_add_co_u32_e32 v44, vcc, s3, v48
	v_mul_f32_e32 v32, v32, v32
	v_max_f32_e32 v52, 0, v54
	v_addc_co_u32_e32 v45, vcc, 0, v49, vcc
	v_cvt_pk_bf16_f32 v32, v32, s0
	v_mul_f32_e32 v52, v52, v52
	v_max_f32_e32 v46, 0, v46
	global_store_short v[44:45], v32, off offset:288
	v_cvt_pk_bf16_f32 v52, v52, s0
	global_store_short v[44:45], v50, off
	v_mul_f32_e32 v46, v46, v46
	v_add_co_u32_e32 v50, vcc, s29, v48
; DI bf16_t f2bf(float x) { return (bf16_t)(cvt_pk(x, 0.f) & 0xffffu); }
; DI float ex2(float x) { return __builtin_amdgcn_exp2f(x); }
;     ...
;     } else if (EPI == EPI_FFN1) {
;         bf16_t* d = (bf16_t*)(p.ws + OFF_U) + (size_t)row0 * 4096 + col;
; #pragma unroll
;         for (int e = 0; e < 4; ++e) { const float t = fmaxf(v[e], 0.f); d[(size_t)e * 4096] = f2bf(t * t); }
; template <int EPI, int K, int LNI = -1>
; DI void ph_gemm(const Params& p, const bf16_t* __restrict__ A, const bf16_t* __restrict__ Bt, int N, float* s_aux) {
;     ...
;             for (int ai = 0; ai < 2; ++ai)
; #pragma unroll
;                 for (int m = 0; m < 4; ++m) {
;                     const int lrow0 = ai * 128 + wr * 64 + m * 16 + fq * 4, row0 = brow + lrow0 + oz;
;                     f32x2 rs[4];
;                     if (EPI == EPI_RESID && LNI >= 0) {
;                         const f32x2* st_ = (const f32x2*)((unsigned char*)p.out + OFFO_STATS) + row0;
; #pragma unroll
;                         for (int e = 0; e < 4; ++e) rs[e] = st_[e];
;                     }
;                     if (EPI == EPI_E5) {
;                         const int idx_ = ((row0 % LT) + 48) & 63; const float lgh = lg_[0][0];
; #pragma unroll
;                         for (int e = 0; e < 4; ++e) rs[e] = (f32x2){ex2(lgh * (float)(idx_ + e + 1)), 0.0625f * ex2(lgh * (float)(63 - idx_ - e))};
;                     }
; #pragma unroll
;                     for (int bj = 0; bj < 2; ++bj)
; #pragma unroll
;                         for (int n = 0; n < 2; ++n) {
;                             float v[4];
; #pragma unroll
;                             for (int e = 0; e < 4; ++e) v[e] = acc[ai][bj][m][n][e];
;                             epi_store<EPI, LNI>(p, row0, bcol + bj * 128 + wc * 32 + n * 16 + fr + oz, lrow0, v, sa, rs, lg_[bj][n], lb_[bj][n]);
;                         }
	v_max_f32_e32 v32, 0, v34
	global_store_short v[66:67], v52, off offset:256
	v_cvt_pk_bf16_f32 v46, v46, s0
	v_addc_co_u32_e32 v51, vcc, 0, v49, vcc
	v_mul_f32_e32 v32, v32, v32
	v_max_f32_e32 v52, 0, v55
	global_store_short v[50:51], v46, off
	v_cvt_pk_bf16_f32 v32, v32, s0
	v_mul_f32_e32 v52, v52, v52
	v_max_f32_e32 v46, 0, v47
	global_store_short v[50:51], v32, off offset:288
	v_cvt_pk_bf16_f32 v52, v52, s0
	v_mul_f32_e32 v46, v46, v46
	v_max_f32_e32 v32, 0, v35
	global_store_short v[62:63], v52, off offset:256
	v_cvt_pk_bf16_f32 v52, v46, s0
	v_add_co_u32_e32 v46, vcc, s35, v48
	v_mul_f32_e32 v32, v32, v32
	s_nop 0
	v_addc_co_u32_e32 v47, vcc, 0, v49, vcc
	v_cvt_pk_bf16_f32 v32, v32, s0
	global_store_short v[46:47], v32, off offset:288
	v_add_u32_e32 v32, 0xa0, v136
	v_max_f32_e32 v36, 0, v36
	v_ashrrev_i32_e32 v33, 31, v32
	v_mul_f32_e32 v36, v36, v36
	v_lshlrev_b64 v[32:33], 13, v[32:33]
	v_max_f32_e32 v28, 0, v28
	v_cvt_pk_bf16_f32 v36, v36, s0
	v_lshl_add_u64 v[32:33], s[36:37], 0, v[32:33]
	v_mul_f32_e32 v28, v28, v28
	v_max_f32_e32 v16, 0, v16
	global_store_short v[48:49], v36, off offset:256
	v_lshl_add_u64 v[32:33], v[32:33], 0, v[138:139]
	v_cvt_pk_bf16_f32 v28, v28, s0
	v_mul_f32_e32 v16, v16, v16
	v_max_f32_e32 v36, 0, v37
	global_store_short v[32:33], v28, off
	v_cvt_pk_bf16_f32 v16, v16, s0
	v_mul_f32_e32 v36, v36, v36
	v_max_f32_e32 v28, 0, v29
	global_store_short v[32:33], v16, off offset:288
	v_cvt_pk_bf16_f32 v36, v36, s0
	v_mul_f32_e32 v28, v28, v28
	v_max_f32_e32 v16, 0, v17
	global_store_short v[44:45], v36, off offset:256
	v_cvt_pk_bf16_f32 v34, v28, s0
	v_add_co_u32_e32 v28, vcc, s3, v32
	v_mul_f32_e32 v16, v16, v16
	v_max_f32_e32 v36, 0, v38
	v_addc_co_u32_e32 v29, vcc, 0, v33, vcc
	v_cvt_pk_bf16_f32 v16, v16, s0
	v_mul_f32_e32 v36, v36, v36
	v_max_f32_e32 v30, 0, v30
	global_store_short v[28:29], v16, off offset:288
	v_cvt_pk_bf16_f32 v36, v36, s0
	global_store_short v[28:29], v34, off
	v_mul_f32_e32 v30, v30, v30
	v_add_co_u32_e32 v34, vcc, s29, v32
	v_max_f32_e32 v16, 0, v18
	global_store_short v[50:51], v36, off offset:256
	v_cvt_pk_bf16_f32 v30, v30, s0
	v_addc_co_u32_e32 v35, vcc, 0, v33, vcc
	v_mul_f32_e32 v16, v16, v16
	v_max_f32_e32 v36, 0, v39
	global_store_short v[34:35], v30, off
	v_cvt_pk_bf16_f32 v16, v16, s0
	v_mul_f32_e32 v36, v36, v36
	v_max_f32_e32 v30, 0, v31
	global_store_short v[34:35], v16, off offset:288
	v_cvt_pk_bf16_f32 v36, v36, s0
	v_mul_f32_e32 v30, v30, v30
	v_max_f32_e32 v16, 0, v19
	global_store_short v[46:47], v36, off offset:256
	v_cvt_pk_bf16_f32 v36, v30, s0
	v_add_co_u32_e32 v30, vcc, s35, v32
	v_mul_f32_e32 v16, v16, v16
	s_nop 0
	v_addc_co_u32_e32 v31, vcc, 0, v33, vcc
	v_cvt_pk_bf16_f32 v16, v16, s0
	v_max_f32_e32 v20, 0, v20
	global_store_short v[30:31], v16, off offset:288
	v_add_u32_e32 v16, 0xb0, v136
	v_mul_f32_e32 v20, v20, v20
	v_ashrrev_i32_e32 v17, 31, v16
	v_cvt_pk_bf16_f32 v20, v20, s0
	v_lshlrev_b64 v[16:17], 13, v[16:17]
	v_max_f32_e32 v12, 0, v12
	v_max_f32_e32 v120, 0, v120
	v_max_f32_e32 v104, 0, v104
	v_max_f32_e32 v88, 0, v88
	v_max_f32_e32 v72, 0, v72
	v_max_f32_e32 v56, 0, v56
	v_max_f32_e32 v40, 0, v40
	v_max_f32_e32 v24, 0, v24
	global_store_short v[32:33], v20, off offset:256
	v_lshl_add_u64 v[16:17], s[36:37], 0, v[16:17]
	v_mul_f32_e32 v12, v12, v12
	v_max_f32_e32 v8, 0, v8
	v_max_f32_e32 v4, 0, v4
	v_max_f32_e32 v0, 0, v0
	v_mul_f32_e32 v120, v120, v120
	v_mul_f32_e32 v104, v104, v104
	v_mul_f32_e32 v88, v88, v88
	v_mul_f32_e32 v72, v72, v72
	v_mul_f32_e32 v56, v56, v56
	v_mul_f32_e32 v40, v40, v40
	v_mul_f32_e32 v24, v24, v24
	v_max_f32_e32 v20, 0, v21
	v_lshl_add_u64 v[16:17], v[16:17], 0, v[138:139]
	v_cvt_pk_bf16_f32 v12, v12, s0
	v_mul_f32_e32 v8, v8, v8
	v_mul_f32_e32 v4, v4, v4
	v_mul_f32_e32 v0, v0, v0
	v_cvt_pk_bf16_f32 v120, v120, s0
	v_cvt_pk_bf16_f32 v104, v104, s0
	v_cvt_pk_bf16_f32 v88, v88, s0
	v_cvt_pk_bf16_f32 v72, v72, s0
	v_cvt_pk_bf16_f32 v56, v56, s0
	v_cvt_pk_bf16_f32 v40, v40, s0
	v_cvt_pk_bf16_f32 v24, v24, s0
	v_mul_f32_e32 v20, v20, v20
	global_store_short v[16:17], v12, off
	v_cvt_pk_bf16_f32 v8, v8, s0
	v_cvt_pk_bf16_f32 v4, v4, s0
	v_cvt_pk_bf16_f32 v0, v0, s0
	global_store_short v[166:167], v120, off offset:32
	global_store_short v[112:113], v104, off offset:32
	global_store_short v[96:97], v88, off offset:32
	global_store_short v[80:81], v72, off offset:32
	global_store_short v[64:65], v56, off offset:32
	global_store_short v[48:49], v40, off offset:32
	global_store_short v[32:33], v24, off offset:32
	v_cvt_pk_bf16_f32 v20, v20, s0
	v_max_f32_e32 v12, 0, v13
	global_store_short v[16:17], v8, off offset:32
	global_store_short v[16:17], v4, off offset:256
	global_store_short v[16:17], v0, off offset:288
	v_max_f32_e32 v120, 0, v121
	v_max_f32_e32 v104, 0, v105
	v_max_f32_e32 v88, 0, v89
	v_max_f32_e32 v72, 0, v73
	v_max_f32_e32 v56, 0, v57
	v_max_f32_e32 v40, 0, v41
	v_max_f32_e32 v24, 0, v25
	global_store_short v[28:29], v20, off offset:256
	v_mul_f32_e32 v12, v12, v12
	v_max_f32_e32 v8, 0, v9
	v_max_f32_e32 v4, 0, v5
	v_max_f32_e32 v0, 0, v1
	v_mul_f32_e32 v120, v120, v120
	v_mul_f32_e32 v104, v104, v104
; DI bf16_t f2bf(float x) { return (bf16_t)(cvt_pk(x, 0.f) & 0xffffu); }
; DI float ex2(float x) { return __builtin_amdgcn_exp2f(x); }
; #define BAR __builtin_amdgcn_s_barrier()
;     ...
;     } else if (EPI == EPI_FFN1) {
;         bf16_t* d = (bf16_t*)(p.ws + OFF_U) + (size_t)row0 * 4096 + col;
; #pragma unroll
;         for (int e = 0; e < 4; ++e) { const float t = fmaxf(v[e], 0.f); d[(size_t)e * 4096] = f2bf(t * t); }
; template <int EPI, int K, int LNI = -1>
; DI void ph_gemm(const Params& p, const bf16_t* __restrict__ A, const bf16_t* __restrict__ Bt, int N, float* s_aux) {
;     ...
;             for (int ai = 0; ai < 2; ++ai)
; #pragma unroll
;                 for (int m = 0; m < 4; ++m) {
;                     const int lrow0 = ai * 128 + wr * 64 + m * 16 + fq * 4, row0 = brow + lrow0 + oz;
;                     f32x2 rs[4];
;                     if (EPI == EPI_RESID && LNI >= 0) {
;                         const f32x2* st_ = (const f32x2*)((unsigned char*)p.out + OFFO_STATS) + row0;
; #pragma unroll
;                         for (int e = 0; e < 4; ++e) rs[e] = st_[e];
;                     }
;                     if (EPI == EPI_E5) {
;                         const int idx_ = ((row0 % LT) + 48) & 63; const float lgh = lg_[0][0];
; #pragma unroll
;                         for (int e = 0; e < 4; ++e) rs[e] = (f32x2){ex2(lgh * (float)(idx_ + e + 1)), 0.0625f * ex2(lgh * (float)(63 - idx_ - e))};
;                     }
; #pragma unroll
;                     for (int bj = 0; bj < 2; ++bj)
; #pragma unroll
;                         for (int n = 0; n < 2; ++n) {
;                             float v[4];
; #pragma unroll
;                             for (int e = 0; e < 4; ++e) v[e] = acc[ai][bj][m][n][e];
;                             epi_store<EPI, LNI>(p, row0, bcol + bj * 128 + wc * 32 + n * 16 + fr + oz, lrow0, v, sa, rs, lg_[bj][n], lb_[bj][n]);
;                         }
;                 }
;         }
;         if (!has_next) break;
; #pragma unroll
;         for (int a = 0; a < 2; ++a)
; #pragma unroll
;             for (int b = 0; b < 2; ++b)
; #pragma unroll
;                 for (int m = 0; m < 4; ++m)
; #pragma unroll
;                     for (int n = 0; n < 2; ++n) acc[a][b][m][n] = (f32x4){0.f, 0.f, 0.f, 0.f};
;         pm = npm; pn = npn; cA = nA; cB = nB; it = itn; ++cnt;
;         if (wr == 1) BAR;
;     }
	v_mul_f32_e32 v88, v88, v88
	v_mul_f32_e32 v72, v72, v72
	v_mul_f32_e32 v56, v56, v56
	v_mul_f32_e32 v40, v40, v40
	v_mul_f32_e32 v24, v24, v24
	v_max_f32_e32 v20, 0, v22
	v_cvt_pk_bf16_f32 v18, v12, s0
	v_add_co_u32_e32 v12, vcc, s3, v16
	s_nop 1
	v_mul_f32_e32 v8, v8, v8
	v_mul_f32_e32 v4, v4, v4
	v_mul_f32_e32 v0, v0, v0
	v_cvt_pk_bf16_f32 v120, v120, s0
	v_cvt_pk_bf16_f32 v104, v104, s0
	v_cvt_pk_bf16_f32 v88, v88, s0
	v_cvt_pk_bf16_f32 v72, v72, s0
	v_cvt_pk_bf16_f32 v56, v56, s0
	v_cvt_pk_bf16_f32 v40, v40, s0
	v_cvt_pk_bf16_f32 v24, v24, s0
	v_mul_f32_e32 v20, v20, v20
	v_addc_co_u32_e32 v13, vcc, 0, v17, vcc
	v_max_f32_e32 v14, 0, v14
	v_cvt_pk_bf16_f32 v8, v8, s0
	v_cvt_pk_bf16_f32 v4, v4, s0
	v_cvt_pk_bf16_f32 v0, v0, s0
	global_store_short v[124:125], v120, off offset:32
	global_store_short v[108:109], v104, off offset:32
	global_store_short v[92:93], v88, off offset:32
	global_store_short v[76:77], v72, off offset:32
	global_store_short v[60:61], v56, off offset:32
	global_store_short v[44:45], v40, off offset:32
	global_store_short v[28:29], v24, off offset:32
	v_cvt_pk_bf16_f32 v20, v20, s0
	global_store_short v[12:13], v18, off
	v_mul_f32_e32 v14, v14, v14
	v_add_co_u32_e32 v18, vcc, s29, v16
	global_store_short v[12:13], v8, off offset:32
	global_store_short v[12:13], v4, off offset:256
	global_store_short v[12:13], v0, off offset:288
	v_max_f32_e32 v120, 0, v122
	v_max_f32_e32 v104, 0, v106
	v_max_f32_e32 v88, 0, v90
	v_max_f32_e32 v72, 0, v74
	v_max_f32_e32 v56, 0, v58
	v_max_f32_e32 v40, 0, v42
	v_max_f32_e32 v24, 0, v26
	global_store_short v[34:35], v20, off offset:256
	v_cvt_pk_bf16_f32 v14, v14, s0
	v_addc_co_u32_e32 v19, vcc, 0, v17, vcc
	v_max_f32_e32 v8, 0, v10
	v_max_f32_e32 v4, 0, v6
	v_max_f32_e32 v0, 0, v2
	v_mul_f32_e32 v120, v120, v120
	v_mul_f32_e32 v104, v104, v104
	v_mul_f32_e32 v88, v88, v88
	v_mul_f32_e32 v72, v72, v72
	v_mul_f32_e32 v56, v56, v56
	v_mul_f32_e32 v40, v40, v40
	v_mul_f32_e32 v24, v24, v24
	v_max_f32_e32 v20, 0, v23
	global_store_short v[18:19], v14, off
	v_mul_f32_e32 v8, v8, v8
	v_mul_f32_e32 v4, v4, v4
	v_mul_f32_e32 v0, v0, v0
	v_cvt_pk_bf16_f32 v120, v120, s0
	v_cvt_pk_bf16_f32 v104, v104, s0
	v_cvt_pk_bf16_f32 v88, v88, s0
	v_cvt_pk_bf16_f32 v72, v72, s0
	v_cvt_pk_bf16_f32 v56, v56, s0
	v_cvt_pk_bf16_f32 v40, v40, s0
	v_cvt_pk_bf16_f32 v24, v24, s0
	v_mul_f32_e32 v20, v20, v20
	v_max_f32_e32 v14, 0, v15
	v_cvt_pk_bf16_f32 v8, v8, s0
	v_cvt_pk_bf16_f32 v4, v4, s0
	v_cvt_pk_bf16_f32 v0, v0, s0
	global_store_short v[168:169], v120, off offset:32
	global_store_short v[114:115], v104, off offset:32
	global_store_short v[98:99], v88, off offset:32
	global_store_short v[82:83], v72, off offset:32
	global_store_short v[66:67], v56, off offset:32
	global_store_short v[50:51], v40, off offset:32
	global_store_short v[34:35], v24, off offset:32
	v_cvt_pk_bf16_f32 v20, v20, s0
	v_mul_f32_e32 v14, v14, v14
	global_store_short v[18:19], v8, off offset:32
	global_store_short v[18:19], v4, off offset:256
	global_store_short v[18:19], v0, off offset:288
	v_max_f32_e32 v120, 0, v123
	v_max_f32_e32 v104, 0, v107
	v_max_f32_e32 v88, 0, v91
	v_max_f32_e32 v72, 0, v75
	v_max_f32_e32 v56, 0, v59
	v_max_f32_e32 v40, 0, v43
	v_max_f32_e32 v24, 0, v27
	global_store_short v[30:31], v20, off offset:256
	v_cvt_pk_bf16_f32 v20, v14, s0
	v_add_co_u32_e32 v14, vcc, s35, v16
	v_max_f32_e32 v8, 0, v11
	v_max_f32_e32 v4, 0, v7
	v_max_f32_e32 v0, 0, v3
	v_mul_f32_e32 v120, v120, v120
	v_mul_f32_e32 v104, v104, v104
	v_mul_f32_e32 v88, v88, v88
	v_mul_f32_e32 v72, v72, v72
	v_mul_f32_e32 v56, v56, v56
	v_mul_f32_e32 v40, v40, v40
	v_mul_f32_e32 v24, v24, v24
	v_addc_co_u32_e32 v15, vcc, 0, v17, vcc
	v_mul_f32_e32 v8, v8, v8
	v_mul_f32_e32 v4, v4, v4
	v_mul_f32_e32 v0, v0, v0
	v_cvt_pk_bf16_f32 v120, v120, s0
	v_cvt_pk_bf16_f32 v104, v104, s0
	v_cvt_pk_bf16_f32 v88, v88, s0
	v_cvt_pk_bf16_f32 v72, v72, s0
	v_cvt_pk_bf16_f32 v56, v56, s0
	v_cvt_pk_bf16_f32 v40, v40, s0
	v_cvt_pk_bf16_f32 v24, v24, s0
	v_cvt_pk_bf16_f32 v8, v8, s0
	v_cvt_pk_bf16_f32 v4, v4, s0
	v_cvt_pk_bf16_f32 v0, v0, s0
	s_andn2_b64 vcc, exec, s[14:15]
	s_mov_b64 s[14:15], -1
	global_store_short v[126:127], v137, off
	global_store_short v[126:127], v120, off offset:32
	global_store_short v[110:111], v116, off
	global_store_short v[110:111], v104, off offset:32
	global_store_short v[94:95], v100, off
	global_store_short v[94:95], v88, off offset:32
	global_store_short v[78:79], v84, off
	global_store_short v[78:79], v72, off offset:32
	global_store_short v[62:63], v68, off
	global_store_short v[62:63], v56, off offset:32
	global_store_short v[46:47], v52, off
	global_store_short v[46:47], v40, off offset:32
	global_store_short v[30:31], v36, off
	global_store_short v[30:31], v24, off offset:32
	global_store_short v[14:15], v20, off
	global_store_short v[14:15], v8, off offset:32
	global_store_short v[14:15], v4, off offset:256
	global_store_short v[14:15], v0, off offset:288
	s_cbranch_vccnz .LBB0_1845
	s_and_saveexec_b64 s[14:15], s[6:7]
	s_xor_b64 s[14:15], exec, s[14:15]
	s_cbranch_execz .LBB0_1844
	s_barrier
	s_branch .LBB0_1844
